# banded attention units: K and V pairs requested two pairs ahead through alternating buffers (prefetch stream runs across unit boundaries)
# speedup vs baseline: 1.2662x; 1.0036x over previous
.LBB0_1161:
	s_andn2_b64 vcc, exec, s[0:1]
	s_cbranch_vccnz .LBB0_1273
	v_readlane_b32 s2, v254, 5
	v_readlane_b32 s3, v254, 6
	v_mov_b32_e32 v0, v208
	v_readlane_b32 s5, v254, 0
	s_load_dwordx4 s[40:43], s[2:3], 0xa0
	s_load_dword s4, s[2:3], 0xb0
	s_and_b32 s6, s5, -8
	v_ashrrev_i32_e32 v1, 6, v0
	v_mul_lo_u32 v2, v1, s46
	v_add_u32_e32 v1, s6, v1
	v_readlane_b32 s6, v254, 14
	v_add_u32_e32 v2, s5, v2
	v_readlane_b32 s7, v254, 15
	s_waitcnt lgkmcnt(0)
	s_mov_b64 s[0:1], s[42:43]
	v_cndmask_b32_e64 v49, v2, v1, s[6:7]
	v_readlane_b32 s6, v254, 16
	s_nop 1
	v_cmp_gt_i32_e32 vcc, s6, v49
	s_and_saveexec_b64 s[30:31], vcc
	s_cbranch_execz .LBB0_1215
	s_cmpk_lg_i32 s46, 0x100
	s_cbranch_scc1 .Lband_orig
	s_load_dwordx2 s[6:7], s[2:3], 0x30
	v_readlane_b32 s8, v254, 33
	s_and_b32 s56, s5, 7
	s_lshl_b32 s8, s8, 3
	s_add_i32 s8, s8, s56
	s_lshl_b32 s8, s8, 2
	s_waitcnt lgkmcnt(0)
	s_load_dword s9, s[6:7], s8
	v_lshrrev_b32_e32 v0, 6, v208
	s_waitcnt lgkmcnt(0)
	v_readfirstlane_b32 s1, v0
	s_lshr_b32 s7, s5, 3
	s_lshl_b32 s7, s7, 3
	s_add_i32 s7, s7, s1
	s_lshl_b32 s48, s1, 10
	s_mov_b32 s40, 0x3e38aa3b
	s_mov_b32 s41, 0x3e38aa3b
	s_mov_b32 s57, 0x20400
	s_mul_i32 s0, s1, 0x1200
	s_add_i32 s0, s0, 0x2000
	v_and_b32_e32 v100, 63, v208
	v_lshrrev_b32_e32 v101, 3, v100
	v_mul_u32_u24_e32 v101, 0x90, v101
	v_and_b32_e32 v102, 7, v100
	v_lshl_add_u32 v101, v102, 4, v101
	v_add_u32_e32 v114, s0, v101
	v_bfe_u32 v101, v208, 4, 2
	v_mul_u32_u24_e32 v101, 0x240, v101
	v_and_b32_e32 v102, 15, v208
	v_lshl_add_u32 v101, v102, 1, v101
	v_add_u32_e32 v115, s0, v101
	v_and_b32_e32 v116, 15, v208
	v_bfe_u32 v100, v208, 4, 2
	v_lshlrev_b32_e32 v117, 2, v100
	v_lshlrev_b32_e32 v118, 3, v100
	v_cmp_eq_u32_e32 vcc, 0, v100
	s_nop 1
	v_cndmask_b32_e64 v120, 0, 1.0, vcc
	s_waitcnt lgkmcnt(0)
	v_mov_b32_e32 v119, s9
	v_mul_f32_e32 v119, 0x3fb8aa3b, v119
	s_mov_b32 s6, 0
	s_lshr_b32 s0, s6, 2
	s_cmp_eq_u32 s0, 0
	s_cselect_b32 s3, 1, 0
	s_add_i32 s1, s0, -1
	s_max_i32 s1, s1, 0
	s_lshl_b32 s13, s1, 1
	s_and_b32 s1, s6, 1
	s_lshl_b32 s1, s1, 8
	s_add_i32 s1, s1, s7
	s_lshl_b32 s1, s1, 1
	s_sub_i32 s2, 10, s13
	s_lshr_b32 s14, s1, s2
	s_lshr_b32 s2, 0x400, s13
	s_add_i32 s2, s2, -1
	s_and_b32 s1, s1, s2
	s_lshl_b32 s8, s1, 4
	s_add_i32 s22, s1, 1
	s_sub_i32 s2, 0x80, s3
	s_sub_i32 s2, s8, s2
	s_max_i32 s2, s2, 0
	s_lshr_b32 s2, s2, 4
	s_and_b32 s15, s2, -2
	s_sub_i32 s2, s22, s15
	s_lshr_b32 s2, s2, 1
	s_add_i32 s9, s2, 1
	s_bfe_u32 s2, s6, 0x10001
	s_mul_i32 s2, s2, 0x4800000
	s_mul_i32 s0, s14, 0x1200
	s_add_i32 s2, s2, s0
	s_add_i32 s2, s2, 0xcd00000
	s_add_u32 s86, s42, s2
	s_addc_u32 s87, s43, 0
	s_lshl_b32 s0, 0x12000, s13
	s_mul_i32 s39, s1, s0
	s_lshl_b32 s1, s56, 7
	s_mul_i32 s2, s3, 0x600
	s_sub_i32 s2, 0x600, s2
	s_add_i32 s2, s2, s1
	s_add_i32 s2, s2, s39
	s_add_u32 s62, s86, s2
	s_addc_u32 s63, s87, 0
	s_mov_b32 s10, 0
	v_lshlrev_b32_e32 v90, s13, v116
	v_mul_u32_u24_e32 v90, 0x1200, v90
	v_lshl_add_u32 v204, v118, 1, v90
	global_load_dwordx4 v[16:19], v204, s[62:63]
	global_load_dwordx4 v[20:23], v204, s[62:63] offset:64
	s_lshl_b32 s0, 0x12000, s13
	s_add_u32 s62, s62, s0
	s_addc_u32 s63, s63, 0
	global_load_dwordx4 v[160:163], v204, s[62:63]
	global_load_dwordx4 v[164:167], v204, s[62:63] offset:64
	s_mov_b32 s11, 0
	s_lshr_b32 s0, s11, 2
	s_cmp_eq_u32 s0, 0
	s_cselect_b32 s3, 1, 0
	s_add_i32 s1, s0, -1
	s_max_i32 s1, s1, 0
	s_lshl_b32 s37, s1, 1
	s_and_b32 s1, s11, 1
	s_lshl_b32 s1, s1, 8
	s_add_i32 s1, s1, s7
	s_lshl_b32 s1, s1, 1
	s_sub_i32 s2, 10, s37
	s_lshr_b32 s16, s1, s2
	s_lshr_b32 s2, 0x400, s37
	s_add_i32 s2, s2, -1
	s_and_b32 s1, s1, s2
	s_lshl_b32 s20, s1, 4
	s_add_i32 s36, s1, 1
	s_sub_i32 s2, 0x80, s3
	s_sub_i32 s2, s20, s2
	s_max_i32 s2, s2, 0
	s_lshr_b32 s2, s2, 4
	s_and_b32 s12, s2, -2
	s_sub_i32 s2, s36, s12
	s_lshr_b32 s2, s2, 1
	s_add_i32 s35, s2, 1
	s_bfe_u32 s2, s11, 0x10001
	s_mul_i32 s2, s2, 0x4800000
	s_mul_i32 s0, s16, 0x1200
	s_add_i32 s2, s2, s0
	s_add_i32 s2, s2, 0xcd00000
	s_add_u32 s86, s42, s2
	s_addc_u32 s87, s43, 0
	s_lshl_b32 s0, 0x12000, s37
	s_mul_i32 s39, s1, s0
	s_lshl_b32 s1, s56, 7
	s_lshr_b32 s2, s56, 2
	s_lshl_b32 s2, s2, 7
	s_cmp_eq_u32 s3, 1
	s_cselect_b32 s0, s2, s1
	s_mul_i32 s2, s3, 0x600
	s_sub_i32 s2, 0xa00, s2
	s_add_i32 s2, s2, s0
	s_add_u32 s24, s86, s2
	s_addc_u32 s25, s87, 0
	s_mul_i32 s2, s3, 0x900
	s_sub_i32 s2, 0xe00, s2
	s_add_i32 s2, s2, s0
	s_add_u32 s26, s86, s2
	s_addc_u32 s27, s87, 0
	v_lshlrev_b32_e32 v90, s37, v116
	v_mul_u32_u24_e32 v90, 0x1200, v90
	v_lshl_add_u32 v111, v118, 1, v90
	v_and_b32_e32 v90, 63, v208
	v_and_b32_e32 v123, 7, v90
	v_lshlrev_b32_e32 v123, 4, v123
	v_lshrrev_b32_e32 v90, 3, v90
	v_add_u32_e32 v91, 0, v90
	v_lshlrev_b32_e32 v91, s37, v91
	v_mul_u32_u24_e32 v91, 0x1200, v91
	v_add_u32_e32 v112, v91, v123
	v_add_u32_e32 v91, 8, v90
	v_lshlrev_b32_e32 v91, s37, v91
	v_mul_u32_u24_e32 v91, 0x1200, v91
	v_add_u32_e32 v113, v91, v123
	s_mov_b32 s34, 0
	s_lshl_b32 s1, 0x12000, s37
	s_mul_i32 s0, s12, s1
	s_add_u32 s16, s24, s0
	s_addc_u32 s17, s25, 0
	s_add_u32 s20, s26, s0
	s_addc_u32 s21, s27, 0
	s_add_i32 s2, s12, 1
	s_cmp_gt_i32 s2, s36
	s_cselect_b32 s2, s12, s2
	s_mul_i32 s0, s2, s1
	s_add_u32 s18, s24, s0
	s_addc_u32 s19, s25, 0
	s_add_u32 s22, s26, s0
	s_addc_u32 s23, s27, 0
	global_load_dwordx4 v[24:27], v111, s[16:17]
	global_load_dwordx4 v[28:31], v111, s[16:17] offset:64
	global_load_dwordx4 v[32:35], v111, s[18:19]
	global_load_dwordx4 v[36:39], v111, s[18:19] offset:64
	global_load_dwordx4 v[40:43], v112, s[20:21]
	global_load_dwordx4 v[44:47], v113, s[20:21]
	global_load_dwordx4 v[48:51], v112, s[22:23]
	global_load_dwordx4 v[52:55], v113, s[22:23]
	s_add_i32 s0, s34, 1
	s_cmp_lt_i32 s0, s35
	s_cbranch_scc1 .Lb_pfsamee
	s_cmp_ge_i32 s11, 15
	s_cbranch_scc1 .Lb_pfgoe
	s_add_i32 s11, s11, 1
	s_lshr_b32 s0, s11, 2
	s_cmp_eq_u32 s0, 0
	s_cselect_b32 s3, 1, 0
	s_add_i32 s1, s0, -1
	s_max_i32 s1, s1, 0
	s_lshl_b32 s37, s1, 1
	s_and_b32 s1, s11, 1
	s_lshl_b32 s1, s1, 8
	s_add_i32 s1, s1, s7
	s_lshl_b32 s1, s1, 1
	s_sub_i32 s2, 10, s37
	s_lshr_b32 s16, s1, s2
	s_lshr_b32 s2, 0x400, s37
	s_add_i32 s2, s2, -1
	s_and_b32 s1, s1, s2
	s_lshl_b32 s20, s1, 4
	s_add_i32 s36, s1, 1
	s_sub_i32 s2, 0x80, s3
	s_sub_i32 s2, s20, s2
	s_max_i32 s2, s2, 0
	s_lshr_b32 s2, s2, 4
	s_and_b32 s12, s2, -2
	s_sub_i32 s2, s36, s12
	s_lshr_b32 s2, s2, 1
	s_add_i32 s35, s2, 1
	s_bfe_u32 s2, s11, 0x10001
	s_mul_i32 s2, s2, 0x4800000
	s_mul_i32 s0, s16, 0x1200
	s_add_i32 s2, s2, s0
	s_add_i32 s2, s2, 0xcd00000
	s_add_u32 s86, s42, s2
	s_addc_u32 s87, s43, 0
	s_lshl_b32 s0, 0x12000, s37
	s_mul_i32 s39, s1, s0
	s_lshl_b32 s1, s56, 7
	s_lshr_b32 s2, s56, 2
	s_lshl_b32 s2, s2, 7
	s_cmp_eq_u32 s3, 1
	s_cselect_b32 s0, s2, s1
	s_mul_i32 s2, s3, 0x600
	s_sub_i32 s2, 0xa00, s2
	s_add_i32 s2, s2, s0
	s_add_u32 s24, s86, s2
	s_addc_u32 s25, s87, 0
	s_mul_i32 s2, s3, 0x900
	s_sub_i32 s2, 0xe00, s2
	s_add_i32 s2, s2, s0
	s_add_u32 s26, s86, s2
	s_addc_u32 s27, s87, 0
	v_lshlrev_b32_e32 v90, s37, v116
	v_mul_u32_u24_e32 v90, 0x1200, v90
	v_lshl_add_u32 v111, v118, 1, v90
	v_and_b32_e32 v90, 63, v208
	v_and_b32_e32 v123, 7, v90
	v_lshlrev_b32_e32 v123, 4, v123
	v_lshrrev_b32_e32 v90, 3, v90
	v_add_u32_e32 v91, 0, v90
	v_lshlrev_b32_e32 v91, s37, v91
	v_mul_u32_u24_e32 v91, 0x1200, v91
	v_add_u32_e32 v112, v91, v123
	v_add_u32_e32 v91, 8, v90
	v_lshlrev_b32_e32 v91, s37, v91
	v_mul_u32_u24_e32 v91, 0x1200, v91
	v_add_u32_e32 v113, v91, v123
	s_mov_b32 s34, 0
	s_branch .Lb_pfgoe
.Lb_pfsamee:
	s_mov_b32 s34, s0
	s_add_i32 s12, s12, 2
.Lb_pfgoe:
	s_lshl_b32 s1, 0x12000, s37
	s_mul_i32 s0, s12, s1
	s_add_u32 s16, s24, s0
	s_addc_u32 s17, s25, 0
	s_add_u32 s20, s26, s0
	s_addc_u32 s21, s27, 0
	s_add_i32 s2, s12, 1
	s_cmp_gt_i32 s2, s36
	s_cselect_b32 s2, s12, s2
	s_mul_i32 s0, s2, s1
	s_add_u32 s18, s24, s0
	s_addc_u32 s19, s25, 0
	s_add_u32 s22, s26, s0
	s_addc_u32 s23, s27, 0
	global_load_dwordx4 v[172:175], v111, s[16:17]
	global_load_dwordx4 v[176:179], v111, s[16:17] offset:64
	global_load_dwordx4 v[180:183], v111, s[18:19]
	global_load_dwordx4 v[184:187], v111, s[18:19] offset:64
	global_load_dwordx4 v[188:191], v112, s[20:21]
	global_load_dwordx4 v[192:195], v113, s[20:21]
	global_load_dwordx4 v[196:199], v112, s[22:23]
	global_load_dwordx4 v[200:203], v113, s[22:23]
	s_lshr_b32 s0, s6, 2
	s_cmp_eq_u32 s0, 0
	s_cselect_b32 s2, 1, 0
	s_cselect_b32 s3, 0, 8
	s_sub_i32 s2, 0x80, s2
	s_add_i32 s3, s3, s56
	v_and_b32_e32 v100, 63, v208
	v_lshlrev_b32_e32 v107, 2, v100
	v_add_u32_e32 v107, s48, v107
	v_add_u32_e32 v100, 0xffffffe0, v100
	v_mov_b32_e32 v106, 0xf149f2ca
	s_mov_b32 s0, 4
.Lb_lute:
	v_max_i32_e32 v101, 0, v100
	v_min_i32_e32 v101, 0xff, v101
	v_lshlrev_b32_e32 v101, s13, v101
	v_cvt_f32_u32_e32 v102, v101
	v_mul_f32_e32 v102, 0x3d800000, v102
	v_log_f32_e32 v102, v102
	s_nop 0
	v_mul_f32_e32 v102, 0x40124925, v102
	v_cvt_i32_f32_e32 v102, v102
	v_med3_i32 v102, v102, 0, 15
	v_add_u32_e32 v102, 16, v102
	v_cmp_gt_u32_e32 vcc, 16, v101
	s_nop 1
	v_cndmask_b32_e32 v102, v102, v101, vcc
	v_lshl_add_u32 v102, v102, 4, s3
	v_lshl_add_u32 v102, v102, 2, s57
	ds_read_b32 v102, v102
	v_cmp_ge_u32_e32 vcc, s2, v100
	s_waitcnt lgkmcnt(0)
	v_mul_f32_e32 v102, 0x3fb8aa3b, v102
	v_cndmask_b32_e32 v102, v106, v102, vcc
	ds_write_b32 v107, v102
	v_add_u32_e32 v100, 64, v100
	v_add_u32_e32 v107, 0x100, v107
	s_add_i32 s0, s0, -1
	s_cmp_lg_u32 s0, 0
	s_cbranch_scc1 .Lb_lute
	s_waitcnt lgkmcnt(0)
	s_lshl_b32 s0, s15, 4
	s_sub_i32 s0, s8, s0
	s_add_i32 s0, s0, 13
	s_lshl_b32 s0, s0, 2
	s_add_i32 s0, s0, s48
	v_sub_u32_e32 v110, v116, v117
	v_lshl_add_u32 v110, v110, 2, s0
	s_lshr_b32 s0, s6, 2
	s_cmp_eq_u32 s0, 0
	s_cselect_b64 vcc, -1, 0
	v_mov_b32_e32 v90, 0xefa18f08
	s_nop 1
	v_cndmask_b32_e32 v108, v90, v119, vcc
	v_cndmask_b32_e32 v109, 0, v120, vcc
	v_cndmask_b32_e32 v168, v90, v119, vcc
	v_cndmask_b32_e32 v169, 0, v120, vcc
	v_mov_b32_e32 v0, 0
	v_mov_b32_e32 v1, 0
	v_mov_b32_e32 v2, 0
	v_mov_b32_e32 v3, 0
	v_mov_b32_e32 v4, 0
	v_mov_b32_e32 v5, 0
	v_mov_b32_e32 v6, 0
	v_mov_b32_e32 v7, 0
	v_mov_b32_e32 v8, 0
	v_mov_b32_e32 v9, 0
	v_mov_b32_e32 v10, 0
	v_mov_b32_e32 v11, 0
	v_mov_b32_e32 v12, 0
	v_mov_b32_e32 v13, 0
	v_mov_b32_e32 v14, 0
	v_mov_b32_e32 v15, 0
	v_mov_b32_e32 v144, 0
	v_mov_b32_e32 v145, 0
	v_mov_b32_e32 v146, 0
	v_mov_b32_e32 v147, 0
	v_mov_b32_e32 v148, 0
	v_mov_b32_e32 v149, 0
	v_mov_b32_e32 v150, 0
	v_mov_b32_e32 v151, 0
	v_mov_b32_e32 v152, 0
	v_mov_b32_e32 v153, 0
	v_mov_b32_e32 v154, 0
	v_mov_b32_e32 v155, 0
	v_mov_b32_e32 v156, 0
	v_mov_b32_e32 v157, 0
	v_mov_b32_e32 v158, 0
	v_mov_b32_e32 v159, 0
.Lb_stepA:
	s_waitcnt vmcnt(8)
	ds_write_b128 v114, v[40:43] offset:0
	ds_write_b128 v114, v[44:47] offset:1152
	ds_write_b128 v114, v[48:51] offset:2304
	ds_write_b128 v114, v[52:55] offset:3456
	ds_read_b32 v100, v110 offset:76
	ds_read_b32 v101, v110 offset:72
	ds_read_b32 v102, v110 offset:68
	ds_read_b32 v103, v110 offset:64
	ds_read_b32 v104, v110 offset:12
	ds_read_b32 v105, v110 offset:8
	ds_read_b32 v106, v110 offset:4
	ds_read_b32 v107, v110 offset:0
	ds_read_b32 v124, v110 offset:140
	ds_read_b32 v125, v110 offset:136
	ds_read_b32 v126, v110 offset:132
	ds_read_b32 v127, v110 offset:128
	ds_read_b32 v128, v110 offset:76
	ds_read_b32 v129, v110 offset:72
	ds_read_b32 v130, v110 offset:68
	ds_read_b32 v131, v110 offset:64
	v_add_u32_e32 v110, 0xffffff80, v110
	v_mfma_f32_16x16x32_bf16 v[92:95], v[24:27], v[16:19], 0
	v_mfma_f32_16x16x32_bf16 v[96:99], v[32:35], v[16:19], 0
	v_mfma_f32_16x16x32_bf16 v[92:95], v[28:31], v[20:23], v[92:95]
	v_mfma_f32_16x16x32_bf16 v[96:99], v[36:39], v[20:23], v[96:99]
	v_mfma_f32_16x16x32_bf16 v[132:135], v[24:27], v[160:163], 0
	v_mfma_f32_16x16x32_bf16 v[136:139], v[32:35], v[160:163], 0
	v_mfma_f32_16x16x32_bf16 v[132:135], v[28:31], v[164:167], v[132:135]
	v_mfma_f32_16x16x32_bf16 v[136:139], v[36:39], v[164:167], v[136:139]
	s_mov_b32 s49, 0
	s_add_i32 s1, s10, 1
	s_cmp_ge_i32 s1, s9
	s_cbranch_scc0 .Lb_nolastA
	s_mov_b32 s49, 1
	s_add_i32 s0, s6, 1
	s_min_i32 s0, s0, 15
	s_mov_b32 s15, s0
	s_lshr_b32 s0, s15, 2
	s_cmp_eq_u32 s0, 0
	s_cselect_b32 s3, 1, 0
	s_add_i32 s1, s0, -1
	s_max_i32 s1, s1, 0
	s_lshl_b32 s20, s1, 1
	s_and_b32 s1, s15, 1
	s_lshl_b32 s1, s1, 8
	s_add_i32 s1, s1, s7
	s_lshl_b32 s1, s1, 1
	s_sub_i32 s2, 10, s20
	s_lshr_b32 s21, s1, s2
	s_lshr_b32 s2, 0x400, s20
	s_add_i32 s2, s2, -1
	s_and_b32 s1, s1, s2
	s_lshl_b32 s23, s1, 4
	s_add_i32 s22, s1, 1
	s_sub_i32 s2, 0x80, s3
	s_sub_i32 s2, s23, s2
	s_max_i32 s2, s2, 0
	s_lshr_b32 s2, s2, 4
	s_and_b32 s23, s2, -2
	s_sub_i32 s2, s22, s23
	s_lshr_b32 s2, s2, 1
	s_add_i32 s23, s2, 1
	s_bfe_u32 s2, s15, 0x10001
	s_mul_i32 s2, s2, 0x4800000
	s_mul_i32 s0, s21, 0x1200
	s_add_i32 s2, s2, s0
	s_add_i32 s2, s2, 0xcd00000
	s_add_u32 s86, s42, s2
	s_addc_u32 s87, s43, 0
	s_lshl_b32 s0, 0x12000, s20
	s_mul_i32 s39, s1, s0
	s_lshl_b32 s1, s56, 7
	s_mul_i32 s2, s3, 0x600
	s_sub_i32 s2, 0x600, s2
	s_add_i32 s2, s2, s1
	s_add_i32 s2, s2, s39
	s_add_u32 s62, s86, s2
	s_addc_u32 s63, s87, 0
	v_lshlrev_b32_e32 v90, s20, v116
	v_mul_u32_u24_e32 v90, 0x1200, v90
	v_lshl_add_u32 v204, v118, 1, v90
	global_load_dwordx4 v[16:19], v204, s[62:63]
	global_load_dwordx4 v[20:23], v204, s[62:63] offset:64
	s_lshl_b32 s0, 0x12000, s20
	s_add_u32 s62, s62, s0
	s_addc_u32 s63, s63, 0
	global_load_dwordx4 v[160:163], v204, s[62:63]
	global_load_dwordx4 v[164:167], v204, s[62:63] offset:64
.Lb_nolastA:
	s_add_i32 s0, s34, 1
	s_cmp_lt_i32 s0, s35
	s_cbranch_scc1 .Lb_pfsameA
	s_cmp_ge_i32 s11, 15
	s_cbranch_scc1 .Lb_pfgoA
	s_add_i32 s11, s11, 1
	s_lshr_b32 s0, s11, 2
	s_cmp_eq_u32 s0, 0
	s_cselect_b32 s3, 1, 0
	s_add_i32 s1, s0, -1
	s_max_i32 s1, s1, 0
	s_lshl_b32 s37, s1, 1
	s_and_b32 s1, s11, 1
	s_lshl_b32 s1, s1, 8
	s_add_i32 s1, s1, s7
	s_lshl_b32 s1, s1, 1
	s_sub_i32 s2, 10, s37
	s_lshr_b32 s16, s1, s2
	s_lshr_b32 s2, 0x400, s37
	s_add_i32 s2, s2, -1
	s_and_b32 s1, s1, s2
	s_lshl_b32 s20, s1, 4
	s_add_i32 s36, s1, 1
	s_sub_i32 s2, 0x80, s3
	s_sub_i32 s2, s20, s2
	s_max_i32 s2, s2, 0
	s_lshr_b32 s2, s2, 4
	s_and_b32 s12, s2, -2
	s_sub_i32 s2, s36, s12
	s_lshr_b32 s2, s2, 1
	s_add_i32 s35, s2, 1
	s_bfe_u32 s2, s11, 0x10001
	s_mul_i32 s2, s2, 0x4800000
	s_mul_i32 s0, s16, 0x1200
	s_add_i32 s2, s2, s0
	s_add_i32 s2, s2, 0xcd00000
	s_add_u32 s86, s42, s2
	s_addc_u32 s87, s43, 0
	s_lshl_b32 s0, 0x12000, s37
	s_mul_i32 s39, s1, s0
	s_lshl_b32 s1, s56, 7
	s_lshr_b32 s2, s56, 2
	s_lshl_b32 s2, s2, 7
	s_cmp_eq_u32 s3, 1
	s_cselect_b32 s0, s2, s1
	s_mul_i32 s2, s3, 0x600
	s_sub_i32 s2, 0xa00, s2
	s_add_i32 s2, s2, s0
	s_add_u32 s24, s86, s2
	s_addc_u32 s25, s87, 0
	s_mul_i32 s2, s3, 0x900
	s_sub_i32 s2, 0xe00, s2
	s_add_i32 s2, s2, s0
	s_add_u32 s26, s86, s2
	s_addc_u32 s27, s87, 0
	v_lshlrev_b32_e32 v90, s37, v116
	v_mul_u32_u24_e32 v90, 0x1200, v90
	v_lshl_add_u32 v111, v118, 1, v90
	v_and_b32_e32 v90, 63, v208
	v_and_b32_e32 v123, 7, v90
	v_lshlrev_b32_e32 v123, 4, v123
	v_lshrrev_b32_e32 v90, 3, v90
	v_add_u32_e32 v91, 0, v90
	v_lshlrev_b32_e32 v91, s37, v91
	v_mul_u32_u24_e32 v91, 0x1200, v91
	v_add_u32_e32 v112, v91, v123
	v_add_u32_e32 v91, 8, v90
	v_lshlrev_b32_e32 v91, s37, v91
	v_mul_u32_u24_e32 v91, 0x1200, v91
	v_add_u32_e32 v113, v91, v123
	s_mov_b32 s34, 0
	s_branch .Lb_pfgoA

.Lb_pfgoA:
	s_lshl_b32 s1, 0x12000, s37
	s_mul_i32 s0, s12, s1
	s_add_u32 s16, s24, s0
	s_addc_u32 s17, s25, 0
	s_add_u32 s20, s26, s0
	s_addc_u32 s21, s27, 0
	s_add_i32 s2, s12, 1
	s_cmp_gt_i32 s2, s36
	s_cselect_b32 s2, s12, s2
	s_mul_i32 s0, s2, s1
	s_add_u32 s18, s24, s0
	s_addc_u32 s19, s25, 0
	s_add_u32 s22, s26, s0
	s_addc_u32 s23, s27, 0
	global_load_dwordx4 v[24:27], v111, s[16:17]
	global_load_dwordx4 v[28:31], v111, s[16:17] offset:64
	global_load_dwordx4 v[32:35], v111, s[18:19]
	global_load_dwordx4 v[36:39], v111, s[18:19] offset:64
	global_load_dwordx4 v[40:43], v112, s[20:21]
	global_load_dwordx4 v[44:47], v113, s[20:21]
	global_load_dwordx4 v[48:51], v112, s[22:23]
	global_load_dwordx4 v[52:55], v113, s[22:23]
	s_waitcnt lgkmcnt(0)
	ds_read_u16 v56, v115 offset:0
	ds_read_u16 v74, v115 offset:144
	ds_read_u16 v57, v115 offset:288
	ds_read_u16 v75, v115 offset:432
	ds_read_u16 v60, v115 offset:32
	ds_read_u16 v78, v115 offset:176
	ds_read_u16 v61, v115 offset:320
	ds_read_u16 v79, v115 offset:464
	ds_read_u16 v66, v115 offset:64
	ds_read_u16 v82, v115 offset:208
	ds_read_u16 v67, v115 offset:352
	ds_read_u16 v83, v115 offset:496
	ds_read_u16 v70, v115 offset:96
	ds_read_u16 v86, v115 offset:240
	ds_read_u16 v71, v115 offset:384
	ds_read_u16 v87, v115 offset:528
	ds_read_u16 v58, v115 offset:2304
	ds_read_u16 v76, v115 offset:2448
	ds_read_u16 v59, v115 offset:2592
	ds_read_u16 v77, v115 offset:2736
	ds_read_u16 v62, v115 offset:2336
	ds_read_u16 v80, v115 offset:2480
	ds_read_u16 v63, v115 offset:2624
	ds_read_u16 v81, v115 offset:2768
	ds_read_u16 v68, v115 offset:2368
	ds_read_u16 v84, v115 offset:2512
	ds_read_u16 v69, v115 offset:2656
	ds_read_u16 v85, v115 offset:2800
	ds_read_u16 v72, v115 offset:2400
	ds_read_u16 v88, v115 offset:2544
	ds_read_u16 v73, v115 offset:2688
	ds_read_u16 v89, v115 offset:2832
	v_pk_fma_f32 v[92:93], v[92:93], s[40:41], v[100:101] op_sel_hi:[1,0,1]
	v_pk_fma_f32 v[94:95], v[94:95], s[40:41], v[102:103] op_sel_hi:[1,0,1]
	v_pk_fma_f32 v[96:97], v[96:97], s[40:41], v[104:105] op_sel_hi:[1,0,1]
	v_pk_fma_f32 v[98:99], v[98:99], s[40:41], v[106:107] op_sel_hi:[1,0,1]
	v_max3_f32 v100, v92, v93, v94
	v_max3_f32 v101, v95, v96, v97
	v_max3_f32 v100, v100, v98, v99
	v_max_f32_e32 v100, v100, v101
	v_mov_b32_e32 v101, v100
	s_nop 1
	v_permlane16_swap_b32_e32 v101, v100
	v_max_f32_e32 v100, v100, v101
	v_mov_b32_e32 v101, v100
	s_nop 1
	v_permlane32_swap_b32_e32 v101, v100
	v_max_f32_e32 v102, v100, v101
	v_cmp_gt_f32_e32 vcc, v102, v108
	s_cbranch_vccz .Lb_norescAA
	v_max_f32_e32 v102, v108, v102
	v_sub_f32_e32 v100, v108, v102
	v_exp_f32_e32 v100, v100
	v_mov_b32_e32 v108, v102
	s_nop 0
	v_pk_mul_f32 v[0:1], v[0:1], v[100:101] op_sel_hi:[1,0]
	v_pk_mul_f32 v[2:3], v[2:3], v[100:101] op_sel_hi:[1,0]
	v_pk_mul_f32 v[4:5], v[4:5], v[100:101] op_sel_hi:[1,0]
	v_pk_mul_f32 v[6:7], v[6:7], v[100:101] op_sel_hi:[1,0]
	v_pk_mul_f32 v[8:9], v[8:9], v[100:101] op_sel_hi:[1,0]
	v_pk_mul_f32 v[10:11], v[10:11], v[100:101] op_sel_hi:[1,0]
	v_pk_mul_f32 v[12:13], v[12:13], v[100:101] op_sel_hi:[1,0]
	v_pk_mul_f32 v[14:15], v[14:15], v[100:101] op_sel_hi:[1,0]
	v_mul_f32_e32 v109, v109, v100

.Lb_norescBA:
	v_pk_add_f32 v[132:133], v[132:133], v[168:169] op_sel_hi:[1,0] neg_lo:[0,1] neg_hi:[0,1]
	v_pk_add_f32 v[134:135], v[134:135], v[168:169] op_sel_hi:[1,0] neg_lo:[0,1] neg_hi:[0,1]
	v_pk_add_f32 v[136:137], v[136:137], v[168:169] op_sel_hi:[1,0] neg_lo:[0,1] neg_hi:[0,1]
	v_pk_add_f32 v[138:139], v[138:139], v[168:169] op_sel_hi:[1,0] neg_lo:[0,1] neg_hi:[0,1]
	v_exp_f32_e32 v132, v132
	v_exp_f32_e32 v133, v133
	v_exp_f32_e32 v134, v134
	v_exp_f32_e32 v135, v135
	v_exp_f32_e32 v136, v136
	v_exp_f32_e32 v137, v137
	v_exp_f32_e32 v138, v138
	v_exp_f32_e32 v139, v139
	s_nop 0
	v_pk_add_f32 v[124:125], v[132:133], v[134:135]
	v_pk_add_f32 v[124:125], v[124:125], v[136:137]
	v_pk_add_f32 v[124:125], v[124:125], v[138:139]
	v_add_f32_e32 v124, v124, v125
	v_add_f32_e32 v169, v169, v124
	v_cvt_pk_bf16_f32 v132, v132, v133
	v_cvt_pk_bf16_f32 v133, v134, v135
	v_cvt_pk_bf16_f32 v134, v136, v137
	v_cvt_pk_bf16_f32 v135, v138, v139
	s_nop 1
	v_mfma_f32_16x16x32_bf16 v[144:147], v[56:59], v[132:135], v[144:147]
	v_mfma_f32_16x16x32_bf16 v[148:151], v[60:63], v[132:135], v[148:151]
	v_mfma_f32_16x16x32_bf16 v[152:155], v[66:69], v[132:135], v[152:155]
	v_mfma_f32_16x16x32_bf16 v[156:159], v[70:73], v[132:135], v[156:159]
	s_mov_b32 s38, 1
	s_cmp_eq_u32 s49, 0
	s_cbranch_scc0 .Lb_epilogue
	s_add_i32 s10, s10, 1
	s_branch .Lb_stepB
.Lb_stepB:
	s_waitcnt vmcnt(8)
	ds_write_b128 v114, v[188:191] offset:0
	ds_write_b128 v114, v[192:195] offset:1152
	ds_write_b128 v114, v[196:199] offset:2304
	ds_write_b128 v114, v[200:203] offset:3456
	ds_read_b32 v100, v110 offset:76
	ds_read_b32 v101, v110 offset:72
	ds_read_b32 v102, v110 offset:68
	ds_read_b32 v103, v110 offset:64
	ds_read_b32 v104, v110 offset:12
	ds_read_b32 v105, v110 offset:8
	ds_read_b32 v106, v110 offset:4
	ds_read_b32 v107, v110 offset:0
	ds_read_b32 v124, v110 offset:140
	ds_read_b32 v125, v110 offset:136
	ds_read_b32 v126, v110 offset:132
	ds_read_b32 v127, v110 offset:128
	ds_read_b32 v128, v110 offset:76
	ds_read_b32 v129, v110 offset:72
	ds_read_b32 v130, v110 offset:68
	ds_read_b32 v131, v110 offset:64
	v_add_u32_e32 v110, 0xffffff80, v110
	v_mfma_f32_16x16x32_bf16 v[92:95], v[172:175], v[16:19], 0
	v_mfma_f32_16x16x32_bf16 v[96:99], v[180:183], v[16:19], 0
	v_mfma_f32_16x16x32_bf16 v[92:95], v[176:179], v[20:23], v[92:95]
	v_mfma_f32_16x16x32_bf16 v[96:99], v[184:187], v[20:23], v[96:99]
	v_mfma_f32_16x16x32_bf16 v[132:135], v[172:175], v[160:163], 0
	v_mfma_f32_16x16x32_bf16 v[136:139], v[180:183], v[160:163], 0
	v_mfma_f32_16x16x32_bf16 v[132:135], v[176:179], v[164:167], v[132:135]
	v_mfma_f32_16x16x32_bf16 v[136:139], v[184:187], v[164:167], v[136:139]
	s_mov_b32 s49, 0
	s_add_i32 s1, s10, 1
	s_cmp_ge_i32 s1, s9
	s_cbranch_scc0 .Lb_nolastB
	s_mov_b32 s49, 1
	s_add_i32 s0, s6, 1
	s_min_i32 s0, s0, 15
	s_mov_b32 s15, s0
	s_lshr_b32 s0, s15, 2
	s_cmp_eq_u32 s0, 0
	s_cselect_b32 s3, 1, 0
	s_add_i32 s1, s0, -1
	s_max_i32 s1, s1, 0
	s_lshl_b32 s20, s1, 1
	s_and_b32 s1, s15, 1
	s_lshl_b32 s1, s1, 8
	s_add_i32 s1, s1, s7
	s_lshl_b32 s1, s1, 1
	s_sub_i32 s2, 10, s20
	s_lshr_b32 s21, s1, s2
	s_lshr_b32 s2, 0x400, s20
	s_add_i32 s2, s2, -1
	s_and_b32 s1, s1, s2
	s_lshl_b32 s23, s1, 4
	s_add_i32 s22, s1, 1
	s_sub_i32 s2, 0x80, s3
	s_sub_i32 s2, s23, s2
	s_max_i32 s2, s2, 0
	s_lshr_b32 s2, s2, 4
	s_and_b32 s23, s2, -2
	s_sub_i32 s2, s22, s23
	s_lshr_b32 s2, s2, 1
	s_add_i32 s23, s2, 1
	s_bfe_u32 s2, s15, 0x10001
	s_mul_i32 s2, s2, 0x4800000
	s_mul_i32 s0, s21, 0x1200
	s_add_i32 s2, s2, s0
	s_add_i32 s2, s2, 0xcd00000
	s_add_u32 s86, s42, s2
	s_addc_u32 s87, s43, 0
	s_lshl_b32 s0, 0x12000, s20
	s_mul_i32 s39, s1, s0
	s_lshl_b32 s1, s56, 7
	s_mul_i32 s2, s3, 0x600
	s_sub_i32 s2, 0x600, s2
	s_add_i32 s2, s2, s1
	s_add_i32 s2, s2, s39
	s_add_u32 s62, s86, s2
	s_addc_u32 s63, s87, 0
	v_lshlrev_b32_e32 v90, s20, v116
	v_mul_u32_u24_e32 v90, 0x1200, v90
	v_lshl_add_u32 v204, v118, 1, v90
	global_load_dwordx4 v[16:19], v204, s[62:63]
	global_load_dwordx4 v[20:23], v204, s[62:63] offset:64
	s_lshl_b32 s0, 0x12000, s20
	s_add_u32 s62, s62, s0
	s_addc_u32 s63, s63, 0
	global_load_dwordx4 v[160:163], v204, s[62:63]
	global_load_dwordx4 v[164:167], v204, s[62:63] offset:64

.Lb_pfgoB:
	s_lshl_b32 s1, 0x12000, s37
	s_mul_i32 s0, s12, s1
	s_add_u32 s16, s24, s0
	s_addc_u32 s17, s25, 0
	s_add_u32 s20, s26, s0
	s_addc_u32 s21, s27, 0
	s_add_i32 s2, s12, 1
	s_cmp_gt_i32 s2, s36
	s_cselect_b32 s2, s12, s2
	s_mul_i32 s0, s2, s1
	s_add_u32 s18, s24, s0
	s_addc_u32 s19, s25, 0
	s_add_u32 s22, s26, s0
	s_addc_u32 s23, s27, 0
	global_load_dwordx4 v[172:175], v111, s[16:17]
	global_load_dwordx4 v[176:179], v111, s[16:17] offset:64
	global_load_dwordx4 v[180:183], v111, s[18:19]
	global_load_dwordx4 v[184:187], v111, s[18:19] offset:64
	global_load_dwordx4 v[188:191], v112, s[20:21]
	global_load_dwordx4 v[192:195], v113, s[20:21]
	global_load_dwordx4 v[196:199], v112, s[22:23]
	global_load_dwordx4 v[200:203], v113, s[22:23]
	s_waitcnt lgkmcnt(0)
	ds_read_u16 v56, v115 offset:0
	ds_read_u16 v74, v115 offset:144
	ds_read_u16 v57, v115 offset:288
	ds_read_u16 v75, v115 offset:432
	ds_read_u16 v60, v115 offset:32
	ds_read_u16 v78, v115 offset:176
	ds_read_u16 v61, v115 offset:320
	ds_read_u16 v79, v115 offset:464
	ds_read_u16 v66, v115 offset:64
	ds_read_u16 v82, v115 offset:208
	ds_read_u16 v67, v115 offset:352
	ds_read_u16 v83, v115 offset:496
	ds_read_u16 v70, v115 offset:96
	ds_read_u16 v86, v115 offset:240
	ds_read_u16 v71, v115 offset:384
	ds_read_u16 v87, v115 offset:528
	ds_read_u16 v58, v115 offset:2304
	ds_read_u16 v76, v115 offset:2448
	ds_read_u16 v59, v115 offset:2592
	ds_read_u16 v77, v115 offset:2736
	ds_read_u16 v62, v115 offset:2336
	ds_read_u16 v80, v115 offset:2480
	ds_read_u16 v63, v115 offset:2624
	ds_read_u16 v81, v115 offset:2768
	ds_read_u16 v68, v115 offset:2368
	ds_read_u16 v84, v115 offset:2512
	ds_read_u16 v69, v115 offset:2656
	ds_read_u16 v85, v115 offset:2800
	ds_read_u16 v72, v115 offset:2400
	ds_read_u16 v88, v115 offset:2544
	ds_read_u16 v73, v115 offset:2688
	ds_read_u16 v89, v115 offset:2832
	v_pk_fma_f32 v[92:93], v[92:93], s[40:41], v[100:101] op_sel_hi:[1,0,1]
	v_pk_fma_f32 v[94:95], v[94:95], s[40:41], v[102:103] op_sel_hi:[1,0,1]
	v_pk_fma_f32 v[96:97], v[96:97], s[40:41], v[104:105] op_sel_hi:[1,0,1]
	v_pk_fma_f32 v[98:99], v[98:99], s[40:41], v[106:107] op_sel_hi:[1,0,1]
	v_max3_f32 v100, v92, v93, v94
	v_max3_f32 v101, v95, v96, v97
	v_max3_f32 v100, v100, v98, v99
	v_max_f32_e32 v100, v100, v101
	v_mov_b32_e32 v101, v100
	s_nop 1
	v_permlane16_swap_b32_e32 v101, v100
	v_max_f32_e32 v100, v100, v101
	v_mov_b32_e32 v101, v100
	s_nop 1
	v_permlane32_swap_b32_e32 v101, v100
	v_max_f32_e32 v102, v100, v101
	v_cmp_gt_f32_e32 vcc, v102, v108
	s_cbranch_vccz .Lb_norescAB
	v_max_f32_e32 v102, v108, v102
	v_sub_f32_e32 v100, v108, v102
	v_exp_f32_e32 v100, v100
	v_mov_b32_e32 v108, v102
	s_nop 0
	v_pk_mul_f32 v[0:1], v[0:1], v[100:101] op_sel_hi:[1,0]
	v_pk_mul_f32 v[2:3], v[2:3], v[100:101] op_sel_hi:[1,0]
	v_pk_mul_f32 v[4:5], v[4:5], v[100:101] op_sel_hi:[1,0]
	v_pk_mul_f32 v[6:7], v[6:7], v[100:101] op_sel_hi:[1,0]
	v_pk_mul_f32 v[8:9], v[8:9], v[100:101] op_sel_hi:[1,0]
	v_pk_mul_f32 v[10:11], v[10:11], v[100:101] op_sel_hi:[1,0]
	v_pk_mul_f32 v[12:13], v[12:13], v[100:101] op_sel_hi:[1,0]
	v_pk_mul_f32 v[14:15], v[14:15], v[100:101] op_sel_hi:[1,0]
	v_mul_f32_e32 v109, v109, v100

.Lb_norescBB:
	v_pk_add_f32 v[132:133], v[132:133], v[168:169] op_sel_hi:[1,0] neg_lo:[0,1] neg_hi:[0,1]
	v_pk_add_f32 v[134:135], v[134:135], v[168:169] op_sel_hi:[1,0] neg_lo:[0,1] neg_hi:[0,1]
	v_pk_add_f32 v[136:137], v[136:137], v[168:169] op_sel_hi:[1,0] neg_lo:[0,1] neg_hi:[0,1]
	v_pk_add_f32 v[138:139], v[138:139], v[168:169] op_sel_hi:[1,0] neg_lo:[0,1] neg_hi:[0,1]
	v_exp_f32_e32 v132, v132
	v_exp_f32_e32 v133, v133
	v_exp_f32_e32 v134, v134
	v_exp_f32_e32 v135, v135
	v_exp_f32_e32 v136, v136
	v_exp_f32_e32 v137, v137
	v_exp_f32_e32 v138, v138
	v_exp_f32_e32 v139, v139
	s_nop 0
	v_pk_add_f32 v[124:125], v[132:133], v[134:135]
	v_pk_add_f32 v[124:125], v[124:125], v[136:137]
	v_pk_add_f32 v[124:125], v[124:125], v[138:139]
	v_add_f32_e32 v124, v124, v125
	v_add_f32_e32 v169, v169, v124
	v_cvt_pk_bf16_f32 v132, v132, v133
	v_cvt_pk_bf16_f32 v133, v134, v135
	v_cvt_pk_bf16_f32 v134, v136, v137
	v_cvt_pk_bf16_f32 v135, v138, v139
	s_nop 1
	v_mfma_f32_16x16x32_bf16 v[144:147], v[56:59], v[132:135], v[144:147]
	v_mfma_f32_16x16x32_bf16 v[148:151], v[60:63], v[132:135], v[148:151]
	v_mfma_f32_16x16x32_bf16 v[152:155], v[66:69], v[132:135], v[152:155]
	v_mfma_f32_16x16x32_bf16 v[156:159], v[70:73], v[132:135], v[156:159]
	s_mov_b32 s38, 0
	s_cmp_eq_u32 s49, 0
	s_cbranch_scc0 .Lb_epilogue
	s_add_i32 s10, s10, 1
	s_branch .Lb_stepA

.Lb_ep_storeB:
	v_cvt_pk_bf16_f32 v144, v144, v145
	v_cvt_pk_bf16_f32 v145, v146, v147
	global_store_dwordx2 v121, v[144:145], s[86:87] offset:0
	v_cvt_pk_bf16_f32 v148, v148, v149
	v_cvt_pk_bf16_f32 v149, v150, v151
	global_store_dwordx2 v121, v[148:149], s[86:87] offset:32
	v_cvt_pk_bf16_f32 v152, v152, v153
	v_cvt_pk_bf16_f32 v153, v154, v155
	global_store_dwordx2 v121, v[152:153], s[86:87] offset:64
	v_cvt_pk_bf16_f32 v156, v156, v157
	v_cvt_pk_bf16_f32 v157, v158, v159
	global_store_dwordx2 v121, v[156:157], s[86:87] offset:96
	s_add_i32 s0, s6, 1
	s_cmp_ge_i32 s0, 16
	s_cbranch_scc1 .Lb_exit
	s_lshr_b32 s49, s6, 2
	s_mov_b32 s6, s0
	s_lshr_b32 s0, s6, 2
	s_cmp_eq_u32 s0, 0
	s_cselect_b32 s3, 1, 0
	s_add_i32 s1, s0, -1
	s_max_i32 s1, s1, 0
	s_lshl_b32 s13, s1, 1
	s_and_b32 s1, s6, 1
	s_lshl_b32 s1, s1, 8
	s_add_i32 s1, s1, s7
	s_lshl_b32 s1, s1, 1
	s_sub_i32 s2, 10, s13
	s_lshr_b32 s14, s1, s2
	s_lshr_b32 s2, 0x400, s13
	s_add_i32 s2, s2, -1
	s_and_b32 s1, s1, s2
	s_lshl_b32 s8, s1, 4
	s_add_i32 s22, s1, 1
	s_sub_i32 s2, 0x80, s3
	s_sub_i32 s2, s8, s2
	s_max_i32 s2, s2, 0
	s_lshr_b32 s2, s2, 4
	s_and_b32 s15, s2, -2
	s_sub_i32 s2, s22, s15
	s_lshr_b32 s2, s2, 1
	s_add_i32 s9, s2, 1
	s_mov_b32 s10, 0
	s_lshr_b32 s0, s6, 2
	s_cmp_eq_u32 s0, s49
	s_cbranch_scc1 .Lb_samekind
	s_lshr_b32 s0, s6, 2
	s_cmp_eq_u32 s0, 0
	s_cselect_b32 s2, 1, 0
	s_cselect_b32 s3, 0, 8
	s_sub_i32 s2, 0x80, s2
	s_add_i32 s3, s3, s56
	v_and_b32_e32 v100, 63, v208
	v_lshlrev_b32_e32 v107, 2, v100
	v_add_u32_e32 v107, s48, v107
	v_add_u32_e32 v100, 0xffffffe0, v100
	v_mov_b32_e32 v106, 0xf149f2ca
	s_mov_b32 s0, 4

.Lb_samekind:
	s_lshl_b32 s0, s15, 4
	s_sub_i32 s0, s8, s0
	s_add_i32 s0, s0, 13
	s_lshl_b32 s0, s0, 2
	s_add_i32 s0, s0, s48
	v_sub_u32_e32 v110, v116, v117
	v_lshl_add_u32 v110, v110, 2, s0
	s_lshr_b32 s0, s6, 2
	s_cmp_eq_u32 s0, 0
	s_cselect_b64 vcc, -1, 0
	v_mov_b32_e32 v90, 0xefa18f08
	s_nop 1
	v_cndmask_b32_e32 v108, v90, v119, vcc
	v_cndmask_b32_e32 v109, 0, v120, vcc
	v_cndmask_b32_e32 v168, v90, v119, vcc
	v_cndmask_b32_e32 v169, 0, v120, vcc
	v_mov_b32_e32 v0, 0
	v_mov_b32_e32 v1, 0
	v_mov_b32_e32 v2, 0
	v_mov_b32_e32 v3, 0
	v_mov_b32_e32 v4, 0
	v_mov_b32_e32 v5, 0
	v_mov_b32_e32 v6, 0
	v_mov_b32_e32 v7, 0
	v_mov_b32_e32 v8, 0
	v_mov_b32_e32 v9, 0
	v_mov_b32_e32 v10, 0
	v_mov_b32_e32 v11, 0
	v_mov_b32_e32 v12, 0
	v_mov_b32_e32 v13, 0
	v_mov_b32_e32 v14, 0
	v_mov_b32_e32 v15, 0
	v_mov_b32_e32 v144, 0
	v_mov_b32_e32 v145, 0
	v_mov_b32_e32 v146, 0
	v_mov_b32_e32 v147, 0
	v_mov_b32_e32 v148, 0
	v_mov_b32_e32 v149, 0
	v_mov_b32_e32 v150, 0
	v_mov_b32_e32 v151, 0
	v_mov_b32_e32 v152, 0
	v_mov_b32_e32 v153, 0
	v_mov_b32_e32 v154, 0
	v_mov_b32_e32 v155, 0
	v_mov_b32_e32 v156, 0
	v_mov_b32_e32 v157, 0
	v_mov_b32_e32 v158, 0
	v_mov_b32_e32 v159, 0
	s_cmp_eq_u32 s38, 0
	s_cbranch_scc1 .Lb_stepA
	s_branch .Lb_stepB
